# v052 + down-proj epilogue: b1 column-constant loads issued together with the first batch (one serialized vmcnt(0) round trip less per tile)
# speedup vs baseline: 1.0080x; 1.0023x over previous
; #define PG8_STAGE(bufoff, gbase, voff) do { _Pragma("unroll") for (int _i = 0; _i < 2; ++_i) \
;         __builtin_amdgcn_global_load_lds((const unsigned*)((const char*)(gbase) + (voff)[_i]), (PG8_LAS unsigned*)(lds + (bufoff) + ldsw + _i * 8192), 16, 0, 0); } while (0)
; #define PG8_LDA(dst, b, h) do { _Pragma("unroll") for (int m = 0; m < 4; ++m) _Pragma("unroll") for (int k = 0; k < 2; ++k) dst[m][k] = *(const PG8_LAS bf16x8*)(lds + PG8_SA(b, h) + aoff + m * 2048 + k * 1024); } while (0)
; #define PG8_LDB(dst, b, h) do { _Pragma("unroll") for (int n = 0; n < 2; ++n) _Pragma("unroll") for (int k = 0; k < 2; ++k) dst[n][k] = *(const PG8_LAS bf16x8*)(lds + PG8_SB(b, h) + boff + n * 2048 + k * 1024); } while (0)
; #define PG8_MMA(ai, bj, At, Bt) do { __builtin_amdgcn_s_setprio(1); _Pragma("unroll") for (int m = 0; m < 4; ++m) _Pragma("unroll") for (int n = 0; n < 2; ++n) _Pragma("unroll") for (int k = 0; k < 2; ++k) \
;         acc[ai][bj][m][n] = __builtin_amdgcn_mfma_f32_16x16x32_bf16(Bt[n][k], At[m][k], acc[ai][bj][m][n], 0, 0, 0); __builtin_amdgcn_s_setprio(0); } while (0)
; #define PG8_WAIT_V(n) asm volatile("s_waitcnt vmcnt(" #n ")" ::: "memory")
; #define PG8_WAIT_L(n) asm volatile("s_waitcnt lgkmcnt(" #n ")" ::: "memory")
; #define PG8_BAR __builtin_amdgcn_s_barrier()
; #define PG8_SCHED __builtin_amdgcn_sched_barrier(0)
; template <class Epi, class Sched>
; __device__ __forceinline__ void gemm_phase(PG8_LAS unsigned char* lds, const Gemm g, const Sched& S, const Epi& E) {
;     ...
;             PG8_LDB(B0, 0, 0); PG8_SCHED; PG8_LDA(At, 0, 0); PG8_STAGE(PG8_SA(1, 1), a1 + hstep, voffA);
;             PG8_WAIT_L(8); PG8_BAR; PG8_WAIT_L(0); PG8_MMA(0, 0, At, B0); PG8_BAR; PG8_SCHED;
;             PG8_LDB(B1, 0, 1); PG8_STAGE(PG8_SB(0, 0), b2, voffB);
;             PG8_BAR; PG8_WAIT_L(0); PG8_MMA(0, 1, At, B1); PG8_BAR;
;             PG8_LDA(At, 0, 1); PG8_STAGE(PG8_SA(0, 0), a2, voffA);
;             PG8_BAR; PG8_WAIT_L(0); PG8_MMA(1, 0, At, B0); PG8_BAR; PG8_SCHED;
;             PG8_STAGE(PG8_SB(0, 1), b2 + hstep, voffB);
;             PG8_WAIT_V(6); PG8_BAR; PG8_MMA(1, 1, At, B1); PG8_BAR;
;             PG8_LDB(B0, 1, 0); PG8_SCHED; PG8_LDA(At, 1, 0); PG8_STAGE(PG8_SA(0, 1), a2 + hstep, voffA);
;             PG8_WAIT_L(8); PG8_BAR; PG8_WAIT_L(0); PG8_MMA(0, 0, At, B0); PG8_BAR; PG8_SCHED;
.LBB0_882:
	s_setprio 0
	ds_read_b128 v[108:111], v247
	ds_read_b128 v[112:115], v247 offset:1024
	ds_read_b128 v[124:127], v247 offset:2048
	ds_read_b128 v[128:131], v247 offset:3072
	ds_read_b128 v[144:147], v248
	ds_read_b128 v[148:151], v248 offset:1024
	ds_read_b128 v[152:155], v248 offset:2048
	ds_read_b128 v[156:159], v248 offset:3072
	ds_read_b128 v[160:163], v248 offset:4096
	ds_read_b128 v[164:167], v248 offset:5120
	ds_read_b128 v[168:171], v248 offset:6144
	ds_read_b128 v[172:175], v248 offset:7168
	s_waitcnt lgkmcnt(11)
	ds_read_b128 v[188:191], v249
	ds_read_b128 v[192:195], v249 offset:1024
	ds_read_b128 v[196:199], v249 offset:2048
	ds_read_b128 v[200:203], v249 offset:3072
	s_add_u32 s10, s26, 0xffea0080
	s_addc_u32 s11, s27, -1
	s_cmpk_eq_i32 s69, 0x54
	s_cselect_b32 s31, s1, s11
	s_cselect_b32 s30, s0, s10
	s_cselect_b32 s29, s5, s68
	s_cselect_b32 s28, s4, s67
	s_add_u32 s98, s28, s18
	s_addc_u32 s99, s29, s19
	s_add_u32 s100, s30, s18
	s_addc_u32 s101, s31, s19
	s_add_i32 m0, s40, 0xc000
	s_nop 0
	global_load_lds_dwordx4 v184, s[26:27]
	s_add_i32 m0, s40, 0xe000
	s_nop 0
	global_load_lds_dwordx4 v186, s[26:27]
	s_waitcnt vmcnt(8)
	s_waitcnt lgkmcnt(0)
	s_setprio 1
	s_barrier
	v_mfma_f32_16x16x32_bf16 v[140:143], v[108:111], v[144:147], v[140:143]
	v_mfma_f32_16x16x32_bf16 v[136:139], v[124:127], v[144:147], v[136:139]
	v_mfma_f32_16x16x32_bf16 v[116:119], v[108:111], v[152:155], v[116:119]
	v_mfma_f32_16x16x32_bf16 v[104:107], v[124:127], v[152:155], v[104:107]
	v_mfma_f32_16x16x32_bf16 v[92:95], v[108:111], v[160:163], v[92:95]
	v_mfma_f32_16x16x32_bf16 v[88:91], v[124:127], v[160:163], v[88:91]
	v_mfma_f32_16x16x32_bf16 v[76:79], v[108:111], v[168:171], v[76:79]
	v_mfma_f32_16x16x32_bf16 v[72:75], v[124:127], v[168:171], v[72:75]
	v_mfma_f32_16x16x32_bf16 v[140:143], v[112:115], v[148:151], v[140:143]
	v_mfma_f32_16x16x32_bf16 v[136:139], v[128:131], v[148:151], v[136:139]
	v_mfma_f32_16x16x32_bf16 v[116:119], v[112:115], v[156:159], v[116:119]
	v_mfma_f32_16x16x32_bf16 v[104:107], v[128:131], v[156:159], v[104:107]
	v_mfma_f32_16x16x32_bf16 v[92:95], v[112:115], v[164:167], v[92:95]
	v_mfma_f32_16x16x32_bf16 v[88:91], v[128:131], v[164:167], v[88:91]
	v_mfma_f32_16x16x32_bf16 v[76:79], v[112:115], v[172:175], v[76:79]
	v_mfma_f32_16x16x32_bf16 v[72:75], v[128:131], v[172:175], v[72:75]
	v_mfma_f32_16x16x32_bf16 v[132:135], v[188:191], v[144:147], v[132:135]
	v_mfma_f32_16x16x32_bf16 v[120:123], v[196:199], v[144:147], v[120:123]
	v_mfma_f32_16x16x32_bf16 v[100:103], v[188:191], v[152:155], v[100:103]
	v_mfma_f32_16x16x32_bf16 v[96:99], v[196:199], v[152:155], v[96:99]
	v_mfma_f32_16x16x32_bf16 v[84:87], v[188:191], v[160:163], v[84:87]
	v_mfma_f32_16x16x32_bf16 v[80:83], v[196:199], v[160:163], v[80:83]
	v_mfma_f32_16x16x32_bf16 v[68:71], v[188:191], v[168:171], v[68:71]
	v_mfma_f32_16x16x32_bf16 v[64:67], v[196:199], v[168:171], v[64:67]
	v_mfma_f32_16x16x32_bf16 v[132:135], v[192:195], v[148:151], v[132:135]
	v_mfma_f32_16x16x32_bf16 v[120:123], v[200:203], v[148:151], v[120:123]
	v_mfma_f32_16x16x32_bf16 v[100:103], v[192:195], v[156:159], v[100:103]
	v_mfma_f32_16x16x32_bf16 v[96:99], v[200:203], v[156:159], v[96:99]
	v_mfma_f32_16x16x32_bf16 v[84:87], v[192:195], v[164:167], v[84:87]
	v_mfma_f32_16x16x32_bf16 v[80:83], v[200:203], v[164:167], v[80:83]
	v_mfma_f32_16x16x32_bf16 v[68:71], v[192:195], v[172:175], v[68:71]
	v_mfma_f32_16x16x32_bf16 v[64:67], v[200:203], v[172:175], v[64:67]
	s_barrier
	s_setprio 0
	ds_read_b128 v[144:147], v248 offset:16384
	ds_read_b128 v[148:151], v248 offset:17408
	ds_read_b128 v[152:155], v248 offset:18432
	ds_read_b128 v[156:159], v248 offset:19456
	ds_read_b128 v[160:163], v248 offset:20480
	ds_read_b128 v[164:167], v248 offset:21504
	ds_read_b128 v[168:171], v248 offset:22528
	ds_read_b128 v[172:175], v248 offset:23552
	s_add_i32 s10, s49, s39
	s_mov_b32 m0, s10
	s_nop 0
	global_load_lds_dwordx4 v178, s[28:29]
	s_add_i32 m0, s10, 0x2000
	s_nop 0
	global_load_lds_dwordx4 v182, s[28:29]
	s_mov_b32 m0, s40
	s_nop 0
	global_load_lds_dwordx4 v176, s[30:31]
	s_mov_b32 m0, s41
	s_nop 0
	global_load_lds_dwordx4 v180, s[30:31]
	s_add_u32 s10, s28, 0x160000
	s_addc_u32 s11, s29, 0
	s_add_i32 s33, s50, s39
	s_mov_b32 m0, s33
	s_nop 0
	global_load_lds_dwordx4 v178, s[10:11]
	s_add_i32 m0, s33, 0x2000
	s_nop 0
	global_load_lds_dwordx4 v182, s[10:11]
	s_waitcnt vmcnt(8)
	s_waitcnt lgkmcnt(0)
	s_setprio 1
	s_barrier
	v_mfma_f32_16x16x32_bf16 v[60:63], v[108:111], v[144:147], v[60:63]
	v_mfma_f32_16x16x32_bf16 v[56:59], v[124:127], v[144:147], v[56:59]
	v_mfma_f32_16x16x32_bf16 v[44:47], v[108:111], v[152:155], v[44:47]
	v_mfma_f32_16x16x32_bf16 v[40:43], v[124:127], v[152:155], v[40:43]
	v_mfma_f32_16x16x32_bf16 v[28:31], v[108:111], v[160:163], v[28:31]
	v_mfma_f32_16x16x32_bf16 v[24:27], v[124:127], v[160:163], v[24:27]
	v_mfma_f32_16x16x32_bf16 v[12:15], v[108:111], v[168:171], v[12:15]
	v_mfma_f32_16x16x32_bf16 v[8:11], v[124:127], v[168:171], v[8:11]
	s_add_i32 s33, 0, 0x18000
	v_mfma_f32_16x16x32_bf16 v[60:63], v[112:115], v[148:151], v[60:63]
	v_mfma_f32_16x16x32_bf16 v[56:59], v[128:131], v[148:151], v[56:59]
	v_mfma_f32_16x16x32_bf16 v[44:47], v[112:115], v[156:159], v[44:47]
	v_mfma_f32_16x16x32_bf16 v[40:43], v[128:131], v[156:159], v[40:43]
	v_mfma_f32_16x16x32_bf16 v[28:31], v[112:115], v[164:167], v[28:31]
	v_mfma_f32_16x16x32_bf16 v[24:27], v[128:131], v[164:167], v[24:27]
	v_mfma_f32_16x16x32_bf16 v[12:15], v[112:115], v[172:175], v[12:15]
	v_mfma_f32_16x16x32_bf16 v[8:11], v[128:131], v[172:175], v[8:11]
	v_mfma_f32_16x16x32_bf16 v[52:55], v[188:191], v[144:147], v[52:55]
	v_mfma_f32_16x16x32_bf16 v[48:51], v[196:199], v[144:147], v[48:51]
	v_mfma_f32_16x16x32_bf16 v[36:39], v[188:191], v[152:155], v[36:39]
	v_mfma_f32_16x16x32_bf16 v[32:35], v[196:199], v[152:155], v[32:35]
	v_mfma_f32_16x16x32_bf16 v[20:23], v[188:191], v[160:163], v[20:23]
	v_mfma_f32_16x16x32_bf16 v[16:19], v[196:199], v[160:163], v[16:19]
	v_mfma_f32_16x16x32_bf16 v[4:7], v[188:191], v[168:171], v[4:7]
	v_mfma_f32_16x16x32_bf16 v[0:3], v[196:199], v[168:171], v[0:3]
	v_mfma_f32_16x16x32_bf16 v[52:55], v[192:195], v[148:151], v[52:55]
	v_mfma_f32_16x16x32_bf16 v[48:51], v[200:203], v[148:151], v[48:51]
	v_mfma_f32_16x16x32_bf16 v[36:39], v[192:195], v[156:159], v[36:39]
	v_mfma_f32_16x16x32_bf16 v[32:35], v[200:203], v[156:159], v[32:35]
	v_mfma_f32_16x16x32_bf16 v[20:23], v[192:195], v[164:167], v[20:23]
	v_mfma_f32_16x16x32_bf16 v[16:19], v[200:203], v[164:167], v[16:19]
	v_mfma_f32_16x16x32_bf16 v[4:7], v[192:195], v[172:175], v[4:7]
	v_mfma_f32_16x16x32_bf16 v[0:3], v[200:203], v[172:175], v[0:3]
	s_barrier
; #define PG8_STAGE(bufoff, gbase, voff) do { _Pragma("unroll") for (int _i = 0; _i < 2; ++_i) \
;         __builtin_amdgcn_global_load_lds((const unsigned*)((const char*)(gbase) + (voff)[_i]), (PG8_LAS unsigned*)(lds + (bufoff) + ldsw + _i * 8192), 16, 0, 0); } while (0)
; #define PG8_LDA(dst, b, h) do { _Pragma("unroll") for (int m = 0; m < 4; ++m) _Pragma("unroll") for (int k = 0; k < 2; ++k) dst[m][k] = *(const PG8_LAS bf16x8*)(lds + PG8_SA(b, h) + aoff + m * 2048 + k * 1024); } while (0)
; #define PG8_LDB(dst, b, h) do { _Pragma("unroll") for (int n = 0; n < 2; ++n) _Pragma("unroll") for (int k = 0; k < 2; ++k) dst[n][k] = *(const PG8_LAS bf16x8*)(lds + PG8_SB(b, h) + boff + n * 2048 + k * 1024); } while (0)
; #define PG8_MMA(ai, bj, At, Bt) do { __builtin_amdgcn_s_setprio(1); _Pragma("unroll") for (int m = 0; m < 4; ++m) _Pragma("unroll") for (int n = 0; n < 2; ++n) _Pragma("unroll") for (int k = 0; k < 2; ++k) \
;         acc[ai][bj][m][n] = __builtin_amdgcn_mfma_f32_16x16x32_bf16(Bt[n][k], At[m][k], acc[ai][bj][m][n], 0, 0, 0); __builtin_amdgcn_s_setprio(0); } while (0)
; #define PG8_WAIT_V(n) asm volatile("s_waitcnt vmcnt(" #n ")" ::: "memory")
; #define PG8_WAIT_L(n) asm volatile("s_waitcnt lgkmcnt(" #n ")" ::: "memory")
; #define PG8_BAR __builtin_amdgcn_s_barrier()
; #define PG8_SCHED __builtin_amdgcn_sched_barrier(0)
; template <class Epi, class Sched>
; __device__ __forceinline__ void gemm_phase(PG8_LAS unsigned char* lds, const Gemm g, const Sched& S, const Epi& E) {
;     ...
;             PG8_LDB(B0, 1, 0); PG8_SCHED; PG8_LDA(At, 1, 0); PG8_STAGE(PG8_SA(0, 1), a2 + hstep, voffA);
;             PG8_WAIT_L(8); PG8_BAR; PG8_WAIT_L(0); PG8_MMA(0, 0, At, B0); PG8_BAR; PG8_SCHED;
;             PG8_LDB(B1, 1, 1); PG8_STAGE(PG8_SB(1, 0), b3, voffB);
;             PG8_BAR; PG8_WAIT_L(0); PG8_MMA(0, 1, At, B1); PG8_BAR;
;             PG8_LDA(At, 1, 1); PG8_STAGE(PG8_SA(1, 0), a3, voffA);
;             PG8_BAR; PG8_WAIT_L(0); PG8_MMA(1, 0, At, B0); PG8_BAR; PG8_SCHED;
;             PG8_STAGE(PG8_SB(1, 1), b3 + hstep, voffB);
;             PG8_WAIT_V(6); PG8_BAR; PG8_MMA(1, 1, At, B1); PG8_BAR;
	s_setprio 0
	ds_read_b128 v[108:111], v247 offset:32768
	ds_read_b128 v[112:115], v247 offset:33792
	ds_read_b128 v[124:127], v247 offset:34816
	ds_read_b128 v[128:131], v247 offset:35840
	ds_read_b128 v[144:147], v248 offset:32768
	ds_read_b128 v[148:151], v248 offset:33792
	ds_read_b128 v[152:155], v248 offset:34816
	ds_read_b128 v[156:159], v248 offset:35840
	ds_read_b128 v[160:163], v248 offset:36864
	ds_read_b128 v[164:167], v248 offset:37888
	ds_read_b128 v[168:171], v248 offset:38912
	ds_read_b128 v[172:175], v248 offset:39936
	s_waitcnt lgkmcnt(11)
	ds_read_b128 v[188:191], v249 offset:32768
	ds_read_b128 v[192:195], v249 offset:33792
	ds_read_b128 v[196:199], v249 offset:34816
	ds_read_b128 v[200:203], v249 offset:35840
	s_add_u32 s10, s30, 0x160000
	s_addc_u32 s11, s31, 0
	s_mov_b32 m0, s42
	s_nop 0
	global_load_lds_dwordx4 v176, s[10:11]
	s_mov_b32 m0, s43
	s_nop 0
	global_load_lds_dwordx4 v180, s[10:11]
	s_waitcnt vmcnt(8)
	s_waitcnt lgkmcnt(0)
	s_setprio 1
	s_barrier
	v_mfma_f32_16x16x32_bf16 v[140:143], v[108:111], v[144:147], v[140:143]
	v_mfma_f32_16x16x32_bf16 v[136:139], v[124:127], v[144:147], v[136:139]
	v_mfma_f32_16x16x32_bf16 v[116:119], v[108:111], v[152:155], v[116:119]
	v_mfma_f32_16x16x32_bf16 v[104:107], v[124:127], v[152:155], v[104:107]
	v_mfma_f32_16x16x32_bf16 v[92:95], v[108:111], v[160:163], v[92:95]
	v_mfma_f32_16x16x32_bf16 v[88:91], v[124:127], v[160:163], v[88:91]
	v_mfma_f32_16x16x32_bf16 v[76:79], v[108:111], v[168:171], v[76:79]
	v_mfma_f32_16x16x32_bf16 v[72:75], v[124:127], v[168:171], v[72:75]
	v_mfma_f32_16x16x32_bf16 v[140:143], v[112:115], v[148:151], v[140:143]
	v_mfma_f32_16x16x32_bf16 v[136:139], v[128:131], v[148:151], v[136:139]
	v_mfma_f32_16x16x32_bf16 v[116:119], v[112:115], v[156:159], v[116:119]
	v_mfma_f32_16x16x32_bf16 v[104:107], v[128:131], v[156:159], v[104:107]
	v_mfma_f32_16x16x32_bf16 v[92:95], v[112:115], v[164:167], v[92:95]
	v_mfma_f32_16x16x32_bf16 v[88:91], v[128:131], v[164:167], v[88:91]
	v_mfma_f32_16x16x32_bf16 v[76:79], v[112:115], v[172:175], v[76:79]
	v_mfma_f32_16x16x32_bf16 v[72:75], v[128:131], v[172:175], v[72:75]
	v_mfma_f32_16x16x32_bf16 v[132:135], v[188:191], v[144:147], v[132:135]
	v_mfma_f32_16x16x32_bf16 v[120:123], v[196:199], v[144:147], v[120:123]
	v_mfma_f32_16x16x32_bf16 v[100:103], v[188:191], v[152:155], v[100:103]
	v_mfma_f32_16x16x32_bf16 v[96:99], v[196:199], v[152:155], v[96:99]
	v_mfma_f32_16x16x32_bf16 v[84:87], v[188:191], v[160:163], v[84:87]
	v_mfma_f32_16x16x32_bf16 v[80:83], v[196:199], v[160:163], v[80:83]
	v_mfma_f32_16x16x32_bf16 v[68:71], v[188:191], v[168:171], v[68:71]
	v_mfma_f32_16x16x32_bf16 v[64:67], v[196:199], v[168:171], v[64:67]
	v_mfma_f32_16x16x32_bf16 v[132:135], v[192:195], v[148:151], v[132:135]
	v_mfma_f32_16x16x32_bf16 v[120:123], v[200:203], v[148:151], v[120:123]
	v_mfma_f32_16x16x32_bf16 v[100:103], v[192:195], v[156:159], v[100:103]
	v_mfma_f32_16x16x32_bf16 v[96:99], v[200:203], v[156:159], v[96:99]
	v_mfma_f32_16x16x32_bf16 v[84:87], v[192:195], v[164:167], v[84:87]
	v_mfma_f32_16x16x32_bf16 v[80:83], v[200:203], v[164:167], v[80:83]
	v_mfma_f32_16x16x32_bf16 v[68:71], v[192:195], v[172:175], v[68:71]
	v_mfma_f32_16x16x32_bf16 v[64:67], v[200:203], v[172:175], v[64:67]
	s_barrier
	s_setprio 0
	ds_read_b128 v[144:147], v248 offset:49152
	ds_read_b128 v[148:151], v248 offset:50176
	ds_read_b128 v[152:155], v248 offset:51200
	ds_read_b128 v[156:159], v248 offset:52224
	ds_read_b128 v[160:163], v248 offset:53248
	ds_read_b128 v[164:167], v248 offset:54272
	ds_read_b128 v[168:171], v248 offset:55296
	ds_read_b128 v[172:175], v248 offset:56320
	s_add_i32 s30, 0, 0x1c000
	s_add_i32 s10, s33, s39
	s_mov_b32 m0, s10
	s_nop 0
	global_load_lds_dwordx4 v178, s[98:99]
	s_add_i32 m0, s10, 0x2000
	s_nop 0
	global_load_lds_dwordx4 v182, s[98:99]
	s_mov_b32 m0, s45
	s_nop 0
	global_load_lds_dwordx4 v176, s[100:101]
	s_mov_b32 m0, s46
	s_nop 0
	global_load_lds_dwordx4 v180, s[100:101]
	s_add_u32 s10, s28, 0x160080
	s_addc_u32 s11, s29, 0
	s_add_i32 s28, s30, s39
	s_mov_b32 m0, s28
	s_nop 0
	global_load_lds_dwordx4 v178, s[10:11]
	s_add_i32 m0, s28, 0x2000
	s_nop 0
	global_load_lds_dwordx4 v182, s[10:11]
	s_waitcnt vmcnt(8)
	s_waitcnt lgkmcnt(0)
	s_setprio 1
	s_barrier
	v_mfma_f32_16x16x32_bf16 v[60:63], v[108:111], v[144:147], v[60:63]
	v_mfma_f32_16x16x32_bf16 v[56:59], v[124:127], v[144:147], v[56:59]
	v_mfma_f32_16x16x32_bf16 v[44:47], v[108:111], v[152:155], v[44:47]
	v_mfma_f32_16x16x32_bf16 v[40:43], v[124:127], v[152:155], v[40:43]
	v_mfma_f32_16x16x32_bf16 v[28:31], v[108:111], v[160:163], v[28:31]
	v_mfma_f32_16x16x32_bf16 v[24:27], v[124:127], v[160:163], v[24:27]
	v_mfma_f32_16x16x32_bf16 v[12:15], v[108:111], v[168:171], v[12:15]
	v_mfma_f32_16x16x32_bf16 v[8:11], v[124:127], v[168:171], v[8:11]
	s_add_i32 s69, s69, 2
	s_add_u32 s26, s26, 0x100
	s_addc_u32 s27, s27, 0
	s_add_u32 s67, s67, 0x100
	s_addc_u32 s68, s68, 0
	s_cmpk_gt_u32 s69, 0x55
	v_mfma_f32_16x16x32_bf16 v[60:63], v[112:115], v[148:151], v[60:63]
	v_mfma_f32_16x16x32_bf16 v[56:59], v[128:131], v[148:151], v[56:59]
	v_mfma_f32_16x16x32_bf16 v[44:47], v[112:115], v[156:159], v[44:47]
	v_mfma_f32_16x16x32_bf16 v[40:43], v[128:131], v[156:159], v[40:43]
	v_mfma_f32_16x16x32_bf16 v[28:31], v[112:115], v[164:167], v[28:31]
	v_mfma_f32_16x16x32_bf16 v[24:27], v[128:131], v[164:167], v[24:27]
	v_mfma_f32_16x16x32_bf16 v[12:15], v[112:115], v[172:175], v[12:15]
	v_mfma_f32_16x16x32_bf16 v[8:11], v[128:131], v[172:175], v[8:11]
	v_mfma_f32_16x16x32_bf16 v[52:55], v[188:191], v[144:147], v[52:55]
	v_mfma_f32_16x16x32_bf16 v[48:51], v[196:199], v[144:147], v[48:51]
	v_mfma_f32_16x16x32_bf16 v[36:39], v[188:191], v[152:155], v[36:39]
	v_mfma_f32_16x16x32_bf16 v[32:35], v[196:199], v[152:155], v[32:35]
	v_mfma_f32_16x16x32_bf16 v[20:23], v[188:191], v[160:163], v[20:23]
	v_mfma_f32_16x16x32_bf16 v[16:19], v[196:199], v[160:163], v[16:19]
	v_mfma_f32_16x16x32_bf16 v[4:7], v[188:191], v[168:171], v[4:7]
	v_mfma_f32_16x16x32_bf16 v[0:3], v[196:199], v[168:171], v[0:3]
	v_mfma_f32_16x16x32_bf16 v[52:55], v[192:195], v[148:151], v[52:55]
	v_mfma_f32_16x16x32_bf16 v[48:51], v[200:203], v[148:151], v[48:51]
	v_mfma_f32_16x16x32_bf16 v[36:39], v[192:195], v[156:159], v[36:39]
	v_mfma_f32_16x16x32_bf16 v[32:35], v[200:203], v[156:159], v[32:35]
	v_mfma_f32_16x16x32_bf16 v[20:23], v[192:195], v[164:167], v[20:23]
	v_mfma_f32_16x16x32_bf16 v[16:19], v[200:203], v[164:167], v[16:19]
	v_mfma_f32_16x16x32_bf16 v[4:7], v[192:195], v[172:175], v[4:7]
	v_mfma_f32_16x16x32_bf16 v[0:3], v[200:203], v[172:175], v[0:3]
	s_barrier
;     __device__ __forceinline__ void operator()(const AccT& acc, const pg8::Unit& u, int wr, int wc, int fr, int fq) const {
;         const int row0 = u.pm * 256 + wr * 64 + fr, col0 = u.pn * 256 + wc * 32 + 8 * fq;
;         const float* ga = mod + (u.pm >= 64 ? 12288 : 0) + 5 * 2048;
;         f32x4 gv[2][2], lg[2][2], lbv[2][2];
; #pragma unroll
;         for (int bj = 0; bj < 2; ++bj)
; #pragma unroll
;             for (int n = 0; n < 2; ++n) { const int c = col0 + bj * 128 + n * 4; gv[bj][n] = *(const f32x4*)(ga + c); lg[bj][n] = ALPHA * *(const f32x4*)(g1 + c); lbv[bj][n] = ALPHA * *(const f32x4*)(b1 + c); }
; #pragma unroll
;         for (int ai = 0; ai < 2; ++ai) {
;             u32x4 uraw[4][2]; f32x2 stv[4];
; #pragma unroll
;             for (int m = 0; m < 4; ++m) { const int row = row0 + ai * 128 + m * 16; const size_t off = (size_t)row * D + col0; stv[m] = *(const f32x2*)(stats + 2 * row);
; #pragma unroll
;                 for (int bj = 0; bj < 2; ++bj) uraw[m][bj] = *(const u32x4*)(U1 + off + bj * 128); }
; #pragma unroll
;             for (int m = 0; m < 4; ++m) { const int row = row0 + ai * 128 + m * 16; const size_t off = (size_t)row * D + col0; const f32x2 st = stv[m];
; #pragma unroll
;                 for (int bj = 0; bj < 2; ++bj) { float uf[8]; unpack_h8(uraw[m][bj], uf);
;                     const f32x4 ua = {uf[0], uf[1], uf[2], uf[3]}, ub = {uf[4], uf[5], uf[6], uf[7]};
;                     const f32x4 a = ((ua - st.x) * st.y) * lg[bj][0] + lbv[bj][0] + gv[bj][0] * acc[ai][bj][m][0], b = ((ub - st.x) * st.y) * lg[bj][1] + lbv[bj][1] + gv[bj][1] * acc[ai][bj][m][1];
;                     u32x4 w; w.x = pk_h2(a[0], a[1]); w.y = pk_h2(a[2], a[3]); w.z = pk_h2(b[0], b[1]); w.w = pk_h2(b[2], b[3]);
;                     *(u32x4*)(U2 + off + bj * 128) = w; } }
	s_cbranch_scc0 .LBB0_882
	s_setprio 0
	s_cmp_gt_i32 s65, 63
	s_cselect_b32 s10, 0xc000, 0
	s_add_u32 s10, s58, s10
	v_lshl_or_b32 v156, s66, 8, v246
	s_addc_u32 s11, s59, 0
	s_add_u32 s10, s10, 0x6a0a000
	v_ashrrev_i32_e32 v157, 31, v156
	s_addc_u32 s11, s11, 0
	v_lshlrev_b64 v[144:145], 2, v[156:157]
	v_lshl_add_u64 v[108:109], s[10:11], 0, v[144:145]
	v_lshl_add_u64 v[148:149], s[22:23], 0, v[144:145]
	global_load_dwordx4 v[112:115], v[108:109], off offset:16
	global_load_dwordx4 v[128:131], v[108:109], off
	s_nop 0
	global_load_dwordx4 v[108:111], v[148:149], off offset:16
	global_load_dwordx4 v[124:127], v[148:149], off
	v_lshl_add_u64 v[152:153], s[24:25], 0, v[144:145]
	v_lshl_add_u32 v224, s65, 8, v244
	v_lshlrev_b64 v[220:221], 1, v[156:157]
	v_ashrrev_i32_e32 v225, 31, v224
	v_lshl_add_u64 v[222:223], s[6:7], 0, v[220:221]
	v_lshlrev_b64 v[240:241], 12, v[224:225]
	s_and_b64 vcc, exec, s[2:3]
	s_mov_b32 s66, s51
	s_mov_b32 s65, s64
	s_mov_b64 s[28:29], s[4:5]
	s_mov_b64 s[26:27], s[0:1]
	global_load_dwordx4 v[192:195], v[152:153], off offset:16
	global_load_dwordx4 v[196:199], v[152:153], off
	s_waitcnt vmcnt(0)
	v_pk_mul_f32 v[210:211], v[108:109], s[20:21] op_sel_hi:[1,0]
	v_pk_mul_f32 v[204:205], v[126:127], s[20:21] op_sel_hi:[1,0]
	v_pk_mul_f32 v[206:207], v[124:125], s[20:21] op_sel_hi:[1,0]
	s_nop 0
	s_nop 0
	v_or_b32_e32 v108, 0x80, v156
	v_ashrrev_i32_e32 v109, 31, v108
	v_pk_mul_f32 v[208:209], v[110:111], s[20:21] op_sel_hi:[1,0]
	v_or_b32_e32 v156, 48, v224
	v_ashrrev_i32_e32 v157, 31, v156
	v_lshlrev_b32_e32 v158, 1, v156
	v_ashrrev_i32_e32 v159, 31, v158
	v_lshlrev_b64 v[232:233], 12, v[156:157]
	v_lshl_add_u64 v[158:159], v[158:159], 2, s[8:9]
	v_lshl_add_u64 v[156:157], v[222:223], 0, v[232:233]
	s_nop 0
	v_pk_mul_f32 v[214:215], v[192:193], s[20:21] op_sel_hi:[1,0]
	v_lshl_add_u64 v[124:125], v[108:109], 2, s[10:11]
	v_pk_mul_f32 v[216:217], v[198:199], s[20:21] op_sel_hi:[1,0]
	v_pk_mul_f32 v[218:219], v[196:197], s[20:21] op_sel_hi:[1,0]
	v_pk_mul_f32 v[212:213], v[194:195], s[20:21] op_sel_hi:[1,0]
	global_load_dwordx4 v[108:111], v[124:125], off offset:16
	s_nop 0
	global_load_dwordx4 v[124:127], v[124:125], off
	s_nop 0
	global_load_dwordx4 v[144:147], v[148:149], off offset:528
	s_nop 0
	global_load_dwordx4 v[148:151], v[148:149], off offset:512
	s_waitcnt vmcnt(0)
	v_pk_mul_f32 v[190:191], v[144:145], s[20:21] op_sel_hi:[1,0]
	v_pk_mul_f32 v[196:197], v[150:151], s[20:21] op_sel_hi:[1,0]
	v_pk_mul_f32 v[198:199], v[148:149], s[20:21] op_sel_hi:[1,0]
	global_load_dwordx4 v[148:151], v[152:153], off offset:528
	s_nop 0
	global_load_dwordx4 v[152:155], v[152:153], off offset:512
	v_lshlrev_b32_e32 v144, 1, v224
	v_ashrrev_i32_e32 v145, 31, v144
	v_lshl_add_u64 v[144:145], v[144:145], 2, s[8:9]
	global_load_dwordx2 v[234:235], v[144:145], off
	v_lshl_add_u64 v[144:145], v[222:223], 0, v[240:241]
	global_load_dwordx4 v[172:175], v[144:145], off
	global_load_dwordx4 v[160:163], v[144:145], off offset:256
	v_or_b32_e32 v144, 16, v224
	v_pk_mul_f32 v[188:189], v[146:147], s[20:21] op_sel_hi:[1,0]
	v_ashrrev_i32_e32 v145, 31, v144
	v_lshlrev_b32_e32 v146, 1, v144
	v_ashrrev_i32_e32 v147, 31, v146
	v_lshlrev_b64 v[238:239], 12, v[144:145]
	v_lshl_add_u64 v[146:147], v[146:147], 2, s[8:9]
	v_lshl_add_u64 v[144:145], v[222:223], 0, v[238:239]
	global_load_dwordx2 v[236:237], v[146:147], off
	s_waitcnt vmcnt(0)
	v_pk_mul_f32 v[192:193], v[150:151], s[20:21] op_sel_hi:[1,0]
	v_pk_mul_f32 v[194:195], v[148:149], s[20:21] op_sel_hi:[1,0]
	global_load_dwordx4 v[164:167], v[144:145], off
	global_load_dwordx4 v[148:151], v[144:145], off offset:256
	v_or_b32_e32 v144, 32, v224
	v_ashrrev_i32_e32 v145, 31, v144
	v_lshlrev_b32_e32 v146, 1, v144
	v_ashrrev_i32_e32 v147, 31, v146
	v_lshlrev_b64 v[230:231], 12, v[144:145]
	v_lshl_add_u64 v[146:147], v[146:147], 2, s[8:9]
	v_lshl_add_u64 v[144:145], v[222:223], 0, v[230:231]
	v_pk_mul_f32 v[200:201], v[154:155], s[20:21] op_sel_hi:[1,0]
	v_pk_mul_f32 v[202:203], v[152:153], s[20:21] op_sel_hi:[1,0]
	global_load_dwordx2 v[228:229], v[146:147], off
	global_load_dwordx4 v[152:155], v[144:145], off
	s_nop 0
	global_load_dwordx4 v[144:147], v[144:145], off offset:256
	v_cvt_f32_f16_sdwa v225, v172 dst_sel:DWORD dst_unused:UNUSED_PAD src0_sel:WORD_1
	global_load_dwordx2 v[226:227], v[158:159], off
	global_load_dwordx4 v[168:171], v[156:157], off
	s_nop 0
	global_load_dwordx4 v[156:159], v[156:157], off offset:256
	v_cvt_f32_f16_e32 v172, v172
	v_cvt_f32_f16_sdwa v250, v173 dst_sel:DWORD dst_unused:UNUSED_PAD src0_sel:WORD_1
	v_cvt_f32_f16_e32 v251, v173
	v_cvt_f32_f16_sdwa v252, v174 dst_sel:DWORD dst_unused:UNUSED_PAD src0_sel:WORD_1
	v_cvt_f32_f16_e32 v253, v174
	v_cvt_f32_f16_sdwa v254, v175 dst_sel:DWORD dst_unused:UNUSED_PAD src0_sel:WORD_1
	v_cvt_f32_f16_e32 v243, v175
	v_sub_f32_e32 v172, v172, v234
	v_sub_f32_e32 v173, v225, v234
	v_sub_f32_e32 v174, v251, v234
	v_sub_f32_e32 v175, v250, v234
	v_pk_mul_f32 v[174:175], v[234:235], v[174:175] op_sel:[1,0]
	v_pk_mul_f32 v[172:173], v[234:235], v[172:173] op_sel:[1,0]
	v_pk_fma_f32 v[174:175], v[204:205], v[174:175], v[216:217]
	v_pk_fma_f32 v[172:173], v[206:207], v[172:173], v[218:219]
	v_pk_fma_f32 v[142:143], v[142:143], v[130:131], v[174:175]
	v_pk_fma_f32 v[140:141], v[140:141], v[128:129], v[172:173]
	v_sub_f32_e32 v172, v253, v234
	v_sub_f32_e32 v173, v252, v234
	v_sub_f32_e32 v174, v243, v234
	v_sub_f32_e32 v175, v254, v234
	v_pk_mul_f32 v[174:175], v[234:235], v[174:175] op_sel:[1,0]
	v_pk_mul_f32 v[172:173], v[234:235], v[172:173] op_sel:[1,0]
	v_pk_fma_f32 v[174:175], v[208:209], v[174:175], v[212:213]
;     __device__ __forceinline__ void operator()(const AccT& acc, const pg8::Unit& u, int wr, int wc, int fr, int fq) const {
;     ...
;             for (int m = 0; m < 4; ++m) { const int row = row0 + ai * 128 + m * 16; const size_t off = (size_t)row * D + col0; const f32x2 st = stv[m];
; #pragma unroll
;                 for (int bj = 0; bj < 2; ++bj) { float uf[8]; unpack_h8(uraw[m][bj], uf);
;                     const f32x4 ua = {uf[0], uf[1], uf[2], uf[3]}, ub = {uf[4], uf[5], uf[6], uf[7]};
;                     const f32x4 a = ((ua - st.x) * st.y) * lg[bj][0] + lbv[bj][0] + gv[bj][0] * acc[ai][bj][m][0], b = ((ub - st.x) * st.y) * lg[bj][1] + lbv[bj][1] + gv[bj][1] * acc[ai][bj][m][1];
;                     u32x4 w; w.x = pk_h2(a[0], a[1]); w.y = pk_h2(a[2], a[3]); w.z = pk_h2(b[0], b[1]); w.w = pk_h2(b[2], b[3]);
;                     *(u32x4*)(U2 + off + bj * 128) = w; } }
	v_pk_fma_f32 v[172:173], v[210:211], v[172:173], v[214:215]
	v_pk_fma_f32 v[174:175], v[138:139], v[114:115], v[174:175]
	v_pk_fma_f32 v[138:139], v[136:137], v[112:113], v[172:173]
	v_cvt_pk_f16_f32 v136, v140, v141
	v_lshl_add_u64 v[140:141], s[16:17], 0, v[240:241]
	v_cvt_pk_f16_f32 v137, v142, v143
	v_cvt_pk_f16_f32 v138, v138, v139
	v_cvt_pk_f16_f32 v139, v174, v175
	v_lshl_add_u64 v[140:141], v[140:141], 0, v[220:221]
	global_store_dwordx4 v[140:141], v[136:139], off
	v_cvt_f32_f16_sdwa v142, v162 dst_sel:DWORD dst_unused:UNUSED_PAD src0_sel:WORD_1
	v_cvt_f32_f16_e32 v143, v162
	v_cvt_f32_f16_sdwa v137, v160 dst_sel:DWORD dst_unused:UNUSED_PAD src0_sel:WORD_1
	v_cvt_f32_f16_e32 v136, v160
	v_cvt_f32_f16_sdwa v139, v161 dst_sel:DWORD dst_unused:UNUSED_PAD src0_sel:WORD_1
	v_cvt_f32_f16_e32 v138, v161
	v_cvt_f32_f16_sdwa v160, v163 dst_sel:DWORD dst_unused:UNUSED_PAD src0_sel:WORD_1
	v_cvt_f32_f16_e32 v161, v163
	v_sub_f32_e32 v136, v136, v234
	v_sub_f32_e32 v137, v137, v234
	v_sub_f32_e32 v138, v138, v234
	v_sub_f32_e32 v139, v139, v234
	v_pk_mul_f32 v[138:139], v[234:235], v[138:139] op_sel:[1,0]
	v_pk_mul_f32 v[136:137], v[234:235], v[136:137] op_sel:[1,0]
	v_pk_fma_f32 v[138:139], v[196:197], v[138:139], v[200:201]
	v_pk_fma_f32 v[136:137], v[198:199], v[136:137], v[202:203]
	v_pk_fma_f32 v[134:135], v[134:135], v[126:127], v[138:139]
	v_pk_fma_f32 v[132:133], v[132:133], v[124:125], v[136:137]
	v_sub_f32_e32 v136, v143, v234
	v_sub_f32_e32 v137, v142, v234
	v_sub_f32_e32 v138, v161, v234
	v_sub_f32_e32 v139, v160, v234
	v_pk_mul_f32 v[138:139], v[234:235], v[138:139] op_sel:[1,0]
	v_pk_mul_f32 v[136:137], v[234:235], v[136:137] op_sel:[1,0]
	v_pk_fma_f32 v[138:139], v[188:189], v[138:139], v[192:193]
	v_pk_fma_f32 v[136:137], v[190:191], v[136:137], v[194:195]
	v_pk_fma_f32 v[138:139], v[122:123], v[110:111], v[138:139]
	v_pk_fma_f32 v[122:123], v[120:121], v[108:109], v[136:137]
	v_cvt_pk_f16_f32 v120, v132, v133
	v_cvt_pk_f16_f32 v121, v134, v135
	v_cvt_pk_f16_f32 v122, v122, v123
	v_cvt_pk_f16_f32 v123, v138, v139
	global_store_dwordx4 v[140:141], v[120:123], off offset:256
	s_waitcnt vmcnt(0)
	v_cvt_f32_f16_sdwa v132, v166 dst_sel:DWORD dst_unused:UNUSED_PAD src0_sel:WORD_1
	v_cvt_f32_f16_e32 v133, v166
	v_cvt_f32_f16_sdwa v121, v164 dst_sel:DWORD dst_unused:UNUSED_PAD src0_sel:WORD_1
	v_cvt_f32_f16_e32 v120, v164
	v_cvt_f32_f16_sdwa v123, v165 dst_sel:DWORD dst_unused:UNUSED_PAD src0_sel:WORD_1
	v_cvt_f32_f16_e32 v122, v165
	v_cvt_f32_f16_sdwa v134, v167 dst_sel:DWORD dst_unused:UNUSED_PAD src0_sel:WORD_1
	v_cvt_f32_f16_e32 v135, v167
	v_sub_f32_e32 v120, v120, v236
	v_sub_f32_e32 v121, v121, v236
	v_sub_f32_e32 v122, v122, v236
	v_sub_f32_e32 v123, v123, v236
	v_pk_mul_f32 v[122:123], v[236:237], v[122:123] op_sel:[1,0]
	v_pk_mul_f32 v[120:121], v[236:237], v[120:121] op_sel:[1,0]
	v_pk_fma_f32 v[122:123], v[204:205], v[122:123], v[216:217]
	v_pk_fma_f32 v[120:121], v[206:207], v[120:121], v[218:219]
	v_pk_fma_f32 v[118:119], v[118:119], v[130:131], v[122:123]
	v_pk_fma_f32 v[116:117], v[116:117], v[128:129], v[120:121]
	v_sub_f32_e32 v120, v133, v236
	v_sub_f32_e32 v121, v132, v236
	v_sub_f32_e32 v122, v135, v236
	v_sub_f32_e32 v123, v134, v236
	v_pk_mul_f32 v[122:123], v[236:237], v[122:123] op_sel:[1,0]
	v_pk_mul_f32 v[120:121], v[236:237], v[120:121] op_sel:[1,0]
	v_pk_fma_f32 v[122:123], v[208:209], v[122:123], v[212:213]
	v_pk_fma_f32 v[120:121], v[210:211], v[120:121], v[214:215]
	v_pk_fma_f32 v[122:123], v[106:107], v[114:115], v[122:123]
	v_pk_fma_f32 v[106:107], v[104:105], v[112:113], v[120:121]
	v_cvt_pk_f16_f32 v104, v116, v117
	v_lshl_add_u64 v[116:117], s[16:17], 0, v[238:239]
	v_cvt_pk_f16_f32 v105, v118, v119
	v_cvt_pk_f16_f32 v106, v106, v107
	v_cvt_pk_f16_f32 v107, v122, v123
	v_lshl_add_u64 v[116:117], v[116:117], 0, v[220:221]
	global_store_dwordx4 v[116:117], v[104:107], off
	v_cvt_f32_f16_sdwa v118, v150 dst_sel:DWORD dst_unused:UNUSED_PAD src0_sel:WORD_1
	v_cvt_f32_f16_e32 v119, v150
	v_cvt_f32_f16_sdwa v105, v148 dst_sel:DWORD dst_unused:UNUSED_PAD src0_sel:WORD_1
	v_cvt_f32_f16_e32 v104, v148
	v_cvt_f32_f16_sdwa v107, v149 dst_sel:DWORD dst_unused:UNUSED_PAD src0_sel:WORD_1
	v_cvt_f32_f16_e32 v106, v149
	v_cvt_f32_f16_sdwa v120, v151 dst_sel:DWORD dst_unused:UNUSED_PAD src0_sel:WORD_1
	v_cvt_f32_f16_e32 v121, v151
	v_sub_f32_e32 v104, v104, v236
	v_sub_f32_e32 v105, v105, v236
	v_sub_f32_e32 v106, v106, v236
	v_sub_f32_e32 v107, v107, v236
	v_pk_mul_f32 v[106:107], v[236:237], v[106:107] op_sel:[1,0]
	v_pk_mul_f32 v[104:105], v[236:237], v[104:105] op_sel:[1,0]
	v_pk_fma_f32 v[106:107], v[196:197], v[106:107], v[200:201]
	v_pk_fma_f32 v[104:105], v[198:199], v[104:105], v[202:203]
	v_pk_fma_f32 v[102:103], v[102:103], v[126:127], v[106:107]
	v_pk_fma_f32 v[100:101], v[100:101], v[124:125], v[104:105]
	v_sub_f32_e32 v104, v119, v236
	v_sub_f32_e32 v105, v118, v236
	v_sub_f32_e32 v106, v121, v236
	v_sub_f32_e32 v107, v120, v236
	v_pk_mul_f32 v[106:107], v[236:237], v[106:107] op_sel:[1,0]
	v_pk_mul_f32 v[104:105], v[236:237], v[104:105] op_sel:[1,0]
	v_pk_fma_f32 v[106:107], v[188:189], v[106:107], v[192:193]
	v_pk_fma_f32 v[104:105], v[190:191], v[104:105], v[194:195]
	v_pk_fma_f32 v[106:107], v[98:99], v[110:111], v[106:107]
	v_pk_fma_f32 v[98:99], v[96:97], v[108:109], v[104:105]
	v_cvt_pk_f16_f32 v96, v100, v101
	v_cvt_pk_f16_f32 v97, v102, v103
	v_cvt_pk_f16_f32 v98, v98, v99
	v_cvt_pk_f16_f32 v99, v106, v107
	global_store_dwordx4 v[116:117], v[96:99], off offset:256
	v_cvt_f32_f16_sdwa v100, v154 dst_sel:DWORD dst_unused:UNUSED_PAD src0_sel:WORD_1
	v_cvt_f32_f16_e32 v101, v154
;     __device__ __forceinline__ void operator()(const AccT& acc, const pg8::Unit& u, int wr, int wc, int fr, int fq) const {
;     ...
;             for (int m = 0; m < 4; ++m) { const int row = row0 + ai * 128 + m * 16; const size_t off = (size_t)row * D + col0; const f32x2 st = stv[m];
; #pragma unroll
;                 for (int bj = 0; bj < 2; ++bj) { float uf[8]; unpack_h8(uraw[m][bj], uf);
;                     const f32x4 ua = {uf[0], uf[1], uf[2], uf[3]}, ub = {uf[4], uf[5], uf[6], uf[7]};
;                     const f32x4 a = ((ua - st.x) * st.y) * lg[bj][0] + lbv[bj][0] + gv[bj][0] * acc[ai][bj][m][0], b = ((ub - st.x) * st.y) * lg[bj][1] + lbv[bj][1] + gv[bj][1] * acc[ai][bj][m][1];
;                     u32x4 w; w.x = pk_h2(a[0], a[1]); w.y = pk_h2(a[2], a[3]); w.z = pk_h2(b[0], b[1]); w.w = pk_h2(b[2], b[3]);
;                     *(u32x4*)(U2 + off + bj * 128) = w; } }
	v_cvt_f32_f16_sdwa v97, v152 dst_sel:DWORD dst_unused:UNUSED_PAD src0_sel:WORD_1
	v_cvt_f32_f16_e32 v96, v152
	v_cvt_f32_f16_sdwa v99, v153 dst_sel:DWORD dst_unused:UNUSED_PAD src0_sel:WORD_1
	v_cvt_f32_f16_e32 v98, v153
	v_cvt_f32_f16_sdwa v102, v155 dst_sel:DWORD dst_unused:UNUSED_PAD src0_sel:WORD_1
	v_cvt_f32_f16_e32 v103, v155
	v_sub_f32_e32 v96, v96, v228
	v_sub_f32_e32 v97, v97, v228
	v_sub_f32_e32 v98, v98, v228
	v_sub_f32_e32 v99, v99, v228
	v_pk_mul_f32 v[98:99], v[228:229], v[98:99] op_sel:[1,0]
	v_pk_mul_f32 v[96:97], v[228:229], v[96:97] op_sel:[1,0]
	v_pk_fma_f32 v[98:99], v[204:205], v[98:99], v[216:217]
	v_pk_fma_f32 v[96:97], v[206:207], v[96:97], v[218:219]
	v_pk_fma_f32 v[94:95], v[94:95], v[130:131], v[98:99]
	v_pk_fma_f32 v[92:93], v[92:93], v[128:129], v[96:97]
	v_sub_f32_e32 v96, v101, v228
	v_sub_f32_e32 v97, v100, v228
	v_sub_f32_e32 v98, v103, v228
	v_sub_f32_e32 v99, v102, v228
	v_pk_mul_f32 v[98:99], v[228:229], v[98:99] op_sel:[1,0]
	v_pk_mul_f32 v[96:97], v[228:229], v[96:97] op_sel:[1,0]
	v_pk_fma_f32 v[98:99], v[208:209], v[98:99], v[212:213]
	v_pk_fma_f32 v[96:97], v[210:211], v[96:97], v[214:215]
	v_pk_fma_f32 v[98:99], v[90:91], v[114:115], v[98:99]
	v_pk_fma_f32 v[90:91], v[88:89], v[112:113], v[96:97]
	v_cvt_pk_f16_f32 v88, v92, v93
	v_lshl_add_u64 v[92:93], s[16:17], 0, v[230:231]
	v_cvt_pk_f16_f32 v89, v94, v95
	v_cvt_pk_f16_f32 v90, v90, v91
	v_cvt_pk_f16_f32 v91, v98, v99
	v_lshl_add_u64 v[92:93], v[92:93], 0, v[220:221]
	global_store_dwordx4 v[92:93], v[88:91], off
	v_cvt_f32_f16_sdwa v94, v146 dst_sel:DWORD dst_unused:UNUSED_PAD src0_sel:WORD_1
	v_cvt_f32_f16_e32 v95, v146
	v_cvt_f32_f16_sdwa v89, v144 dst_sel:DWORD dst_unused:UNUSED_PAD src0_sel:WORD_1
	v_cvt_f32_f16_e32 v88, v144
	v_cvt_f32_f16_sdwa v91, v145 dst_sel:DWORD dst_unused:UNUSED_PAD src0_sel:WORD_1
	v_cvt_f32_f16_e32 v90, v145
	v_cvt_f32_f16_sdwa v96, v147 dst_sel:DWORD dst_unused:UNUSED_PAD src0_sel:WORD_1
	v_cvt_f32_f16_e32 v97, v147
	v_sub_f32_e32 v88, v88, v228
	v_sub_f32_e32 v89, v89, v228
	v_sub_f32_e32 v90, v90, v228
	v_sub_f32_e32 v91, v91, v228
	v_pk_mul_f32 v[90:91], v[228:229], v[90:91] op_sel:[1,0]
	v_pk_mul_f32 v[88:89], v[228:229], v[88:89] op_sel:[1,0]
	v_pk_fma_f32 v[90:91], v[196:197], v[90:91], v[200:201]
	v_pk_fma_f32 v[88:89], v[198:199], v[88:89], v[202:203]
	v_pk_fma_f32 v[86:87], v[86:87], v[126:127], v[90:91]
	v_pk_fma_f32 v[84:85], v[84:85], v[124:125], v[88:89]
	v_sub_f32_e32 v88, v95, v228
	v_sub_f32_e32 v89, v94, v228
	v_sub_f32_e32 v90, v97, v228
	v_sub_f32_e32 v91, v96, v228
	v_pk_mul_f32 v[90:91], v[228:229], v[90:91] op_sel:[1,0]
	v_pk_mul_f32 v[88:89], v[228:229], v[88:89] op_sel:[1,0]
	v_pk_fma_f32 v[90:91], v[188:189], v[90:91], v[192:193]
	v_pk_fma_f32 v[88:89], v[190:191], v[88:89], v[194:195]
	v_pk_fma_f32 v[90:91], v[82:83], v[110:111], v[90:91]
	v_pk_fma_f32 v[82:83], v[80:81], v[108:109], v[88:89]
	v_cvt_pk_f16_f32 v80, v84, v85
	v_cvt_pk_f16_f32 v81, v86, v87
	v_cvt_pk_f16_f32 v82, v82, v83
	v_cvt_pk_f16_f32 v83, v90, v91
	global_store_dwordx4 v[92:93], v[80:83], off offset:256
	v_cvt_f32_f16_sdwa v84, v170 dst_sel:DWORD dst_unused:UNUSED_PAD src0_sel:WORD_1
	v_cvt_f32_f16_e32 v85, v170
	v_cvt_f32_f16_sdwa v81, v168 dst_sel:DWORD dst_unused:UNUSED_PAD src0_sel:WORD_1
	v_cvt_f32_f16_e32 v80, v168
	v_cvt_f32_f16_sdwa v83, v169 dst_sel:DWORD dst_unused:UNUSED_PAD src0_sel:WORD_1
	v_cvt_f32_f16_e32 v82, v169
	v_cvt_f32_f16_sdwa v86, v171 dst_sel:DWORD dst_unused:UNUSED_PAD src0_sel:WORD_1
	v_cvt_f32_f16_e32 v87, v171
	v_sub_f32_e32 v80, v80, v226
	v_sub_f32_e32 v81, v81, v226
	v_sub_f32_e32 v82, v82, v226
	v_sub_f32_e32 v83, v83, v226
	v_pk_mul_f32 v[82:83], v[226:227], v[82:83] op_sel:[1,0]
	v_pk_mul_f32 v[80:81], v[226:227], v[80:81] op_sel:[1,0]
	v_pk_fma_f32 v[82:83], v[204:205], v[82:83], v[216:217]
	v_pk_fma_f32 v[80:81], v[206:207], v[80:81], v[218:219]
	v_pk_fma_f32 v[78:79], v[78:79], v[130:131], v[82:83]
	v_pk_fma_f32 v[76:77], v[76:77], v[128:129], v[80:81]
	v_sub_f32_e32 v80, v85, v226
	v_sub_f32_e32 v81, v84, v226
	v_sub_f32_e32 v82, v87, v226
	v_sub_f32_e32 v83, v86, v226
	v_pk_mul_f32 v[82:83], v[226:227], v[82:83] op_sel:[1,0]
	v_pk_mul_f32 v[80:81], v[226:227], v[80:81] op_sel:[1,0]
	v_pk_fma_f32 v[82:83], v[208:209], v[82:83], v[212:213]
	v_pk_fma_f32 v[80:81], v[210:211], v[80:81], v[214:215]
	v_pk_fma_f32 v[82:83], v[74:75], v[114:115], v[82:83]
	v_pk_fma_f32 v[74:75], v[72:73], v[112:113], v[80:81]
	v_cvt_pk_f16_f32 v72, v76, v77
	v_lshl_add_u64 v[76:77], s[16:17], 0, v[232:233]
	v_cvt_pk_f16_f32 v73, v78, v79
	v_cvt_pk_f16_f32 v74, v74, v75
	v_cvt_pk_f16_f32 v75, v82, v83
	v_lshl_add_u64 v[76:77], v[76:77], 0, v[220:221]
	global_store_dwordx4 v[76:77], v[72:75], off
	v_cvt_f32_f16_sdwa v78, v158 dst_sel:DWORD dst_unused:UNUSED_PAD src0_sel:WORD_1
	v_cvt_f32_f16_e32 v79, v158
	v_cvt_f32_f16_sdwa v73, v156 dst_sel:DWORD dst_unused:UNUSED_PAD src0_sel:WORD_1
	v_cvt_f32_f16_e32 v72, v156
	v_cvt_f32_f16_sdwa v75, v157 dst_sel:DWORD dst_unused:UNUSED_PAD src0_sel:WORD_1
	v_cvt_f32_f16_e32 v74, v157
	v_cvt_f32_f16_sdwa v80, v159 dst_sel:DWORD dst_unused:UNUSED_PAD src0_sel:WORD_1
	v_cvt_f32_f16_e32 v81, v159
	v_sub_f32_e32 v72, v72, v226
	v_sub_f32_e32 v73, v73, v226
	v_sub_f32_e32 v74, v74, v226
	v_sub_f32_e32 v75, v75, v226
	v_pk_mul_f32 v[74:75], v[226:227], v[74:75] op_sel:[1,0]
	v_pk_mul_f32 v[72:73], v[226:227], v[72:73] op_sel:[1,0]
	v_pk_fma_f32 v[74:75], v[196:197], v[74:75], v[200:201]
	v_pk_fma_f32 v[72:73], v[198:199], v[72:73], v[202:203]
	v_pk_fma_f32 v[70:71], v[70:71], v[126:127], v[74:75]
	v_pk_fma_f32 v[68:69], v[68:69], v[124:125], v[72:73]
	v_sub_f32_e32 v72, v79, v226
;     __device__ __forceinline__ void operator()(const AccT& acc, const pg8::Unit& u, int wr, int wc, int fr, int fq) const {
;     ...
;         for (int ai = 0; ai < 2; ++ai) {
;             u32x4 uraw[4][2]; f32x2 stv[4];
; #pragma unroll
;             for (int m = 0; m < 4; ++m) { const int row = row0 + ai * 128 + m * 16; const size_t off = (size_t)row * D + col0; stv[m] = *(const f32x2*)(stats + 2 * row);
; #pragma unroll
;                 for (int bj = 0; bj < 2; ++bj) uraw[m][bj] = *(const u32x4*)(U1 + off + bj * 128); }
; #pragma unroll
;             for (int m = 0; m < 4; ++m) { const int row = row0 + ai * 128 + m * 16; const size_t off = (size_t)row * D + col0; const f32x2 st = stv[m];
; #pragma unroll
;                 for (int bj = 0; bj < 2; ++bj) { float uf[8]; unpack_h8(uraw[m][bj], uf);
;                     const f32x4 ua = {uf[0], uf[1], uf[2], uf[3]}, ub = {uf[4], uf[5], uf[6], uf[7]};
;                     const f32x4 a = ((ua - st.x) * st.y) * lg[bj][0] + lbv[bj][0] + gv[bj][0] * acc[ai][bj][m][0], b = ((ub - st.x) * st.y) * lg[bj][1] + lbv[bj][1] + gv[bj][1] * acc[ai][bj][m][1];
;                     u32x4 w; w.x = pk_h2(a[0], a[1]); w.y = pk_h2(a[2], a[3]); w.z = pk_h2(b[0], b[1]); w.w = pk_h2(b[2], b[3]);
;                     *(u32x4*)(U2 + off + bj * 128) = w; } }
	v_sub_f32_e32 v73, v78, v226
	v_sub_f32_e32 v74, v81, v226
	v_sub_f32_e32 v75, v80, v226
	v_pk_mul_f32 v[74:75], v[226:227], v[74:75] op_sel:[1,0]
	v_pk_mul_f32 v[72:73], v[226:227], v[72:73] op_sel:[1,0]
	v_pk_fma_f32 v[74:75], v[188:189], v[74:75], v[192:193]
	v_pk_fma_f32 v[72:73], v[190:191], v[72:73], v[194:195]
	v_pk_fma_f32 v[74:75], v[66:67], v[110:111], v[74:75]
	v_pk_fma_f32 v[66:67], v[64:65], v[108:109], v[72:73]
	v_cvt_pk_f16_f32 v64, v68, v69
	v_cvt_pk_f16_f32 v65, v70, v71
	v_cvt_pk_f16_f32 v66, v66, v67
	v_cvt_pk_f16_f32 v67, v74, v75
	global_store_dwordx4 v[76:77], v[64:67], off offset:256
	s_nop 1
	v_add_u32_e32 v64, 0x80, v224
	v_ashrrev_i32_e32 v65, 31, v64
	v_lshlrev_b32_e32 v66, 1, v64
	v_ashrrev_i32_e32 v67, 31, v66
	v_lshlrev_b64 v[106:107], 12, v[64:65]
	v_lshl_add_u64 v[66:67], v[66:67], 2, s[8:9]
	v_lshl_add_u64 v[64:65], v[222:223], 0, v[106:107]
	global_load_dwordx2 v[104:105], v[66:67], off
	global_load_dwordx4 v[84:87], v[64:65], off
	global_load_dwordx4 v[88:91], v[64:65], off offset:256
	v_add_u32_e32 v64, 0x90, v224
	v_ashrrev_i32_e32 v65, 31, v64
	v_lshlrev_b32_e32 v66, 1, v64
	v_ashrrev_i32_e32 v67, 31, v66
	v_lshlrev_b64 v[118:119], 12, v[64:65]
	v_lshl_add_u64 v[66:67], v[66:67], 2, s[8:9]
	v_lshl_add_u64 v[64:65], v[222:223], 0, v[118:119]
	global_load_dwordx2 v[116:117], v[66:67], off
	global_load_dwordx4 v[92:95], v[64:65], off
	global_load_dwordx4 v[96:99], v[64:65], off offset:256
	v_add_u32_e32 v64, 0xa0, v224
	v_ashrrev_i32_e32 v65, 31, v64
	v_lshlrev_b32_e32 v66, 1, v64
	v_ashrrev_i32_e32 v67, 31, v66
	v_lshlrev_b64 v[82:83], 12, v[64:65]
	v_lshl_add_u64 v[66:67], v[66:67], 2, s[8:9]
	v_lshl_add_u64 v[64:65], v[222:223], 0, v[82:83]
	global_load_dwordx2 v[80:81], v[66:67], off
	global_load_dwordx4 v[100:103], v[64:65], off
	global_load_dwordx4 v[72:75], v[64:65], off offset:256
	v_add_u32_e32 v64, 0xb0, v224
	v_ashrrev_i32_e32 v65, 31, v64
	v_lshlrev_b32_e32 v66, 1, v64
	v_ashrrev_i32_e32 v67, 31, v66
	v_lshlrev_b64 v[78:79], 12, v[64:65]
	v_lshl_add_u64 v[66:67], v[66:67], 2, s[8:9]
	v_lshl_add_u64 v[64:65], v[222:223], 0, v[78:79]
	global_load_dwordx2 v[76:77], v[66:67], off
	global_load_dwordx4 v[68:71], v[64:65], off
	s_nop 0
	global_load_dwordx4 v[64:67], v[64:65], off offset:256
	s_waitcnt vmcnt(0)
	v_cvt_f32_f16_e32 v120, v84
	v_cvt_f32_f16_sdwa v84, v84 dst_sel:DWORD dst_unused:UNUSED_PAD src0_sel:WORD_1
	v_cvt_f32_f16_e32 v121, v85
	v_cvt_f32_f16_sdwa v122, v85 dst_sel:DWORD dst_unused:UNUSED_PAD src0_sel:WORD_1
	v_cvt_f32_f16_e32 v123, v86
	v_cvt_f32_f16_sdwa v132, v86 dst_sel:DWORD dst_unused:UNUSED_PAD src0_sel:WORD_1
	v_cvt_f32_f16_e32 v133, v87
	v_cvt_f32_f16_sdwa v134, v87 dst_sel:DWORD dst_unused:UNUSED_PAD src0_sel:WORD_1
	v_sub_f32_e32 v85, v84, v104
	v_sub_f32_e32 v84, v120, v104
	v_sub_f32_e32 v87, v122, v104
	v_sub_f32_e32 v86, v121, v104
	v_pk_mul_f32 v[86:87], v[104:105], v[86:87] op_sel:[1,0]
	v_pk_mul_f32 v[84:85], v[104:105], v[84:85] op_sel:[1,0]
	v_pk_fma_f32 v[86:87], v[204:205], v[86:87], v[216:217]
	v_pk_fma_f32 v[84:85], v[206:207], v[84:85], v[218:219]
	v_pk_fma_f32 v[62:63], v[62:63], v[130:131], v[86:87]
	v_pk_fma_f32 v[60:61], v[60:61], v[128:129], v[84:85]
	v_sub_f32_e32 v85, v132, v104
	v_sub_f32_e32 v84, v123, v104
	v_sub_f32_e32 v87, v134, v104
	v_sub_f32_e32 v86, v133, v104
	v_pk_mul_f32 v[86:87], v[104:105], v[86:87] op_sel:[1,0]
	v_pk_mul_f32 v[84:85], v[104:105], v[84:85] op_sel:[1,0]
	v_pk_fma_f32 v[86:87], v[208:209], v[86:87], v[212:213]
	v_pk_fma_f32 v[84:85], v[210:211], v[84:85], v[214:215]
	v_pk_fma_f32 v[86:87], v[58:59], v[114:115], v[86:87]
	v_pk_fma_f32 v[58:59], v[56:57], v[112:113], v[84:85]
	v_cvt_pk_f16_f32 v56, v60, v61
	v_lshl_add_u64 v[60:61], s[16:17], 0, v[106:107]
	v_cvt_pk_f16_f32 v57, v62, v63
	v_cvt_pk_f16_f32 v58, v58, v59
	v_cvt_pk_f16_f32 v59, v86, v87
	v_lshl_add_u64 v[60:61], v[60:61], 0, v[220:221]
	global_store_dwordx4 v[60:61], v[56:59], off
	v_cvt_f32_f16_e32 v62, v90
	v_cvt_f32_f16_sdwa v63, v90 dst_sel:DWORD dst_unused:UNUSED_PAD src0_sel:WORD_1
	v_cvt_f32_f16_e32 v56, v88
	v_cvt_f32_f16_sdwa v57, v88 dst_sel:DWORD dst_unused:UNUSED_PAD src0_sel:WORD_1
	v_cvt_f32_f16_e32 v58, v89
	v_cvt_f32_f16_sdwa v59, v89 dst_sel:DWORD dst_unused:UNUSED_PAD src0_sel:WORD_1
	v_cvt_f32_f16_e32 v84, v91
	v_cvt_f32_f16_sdwa v85, v91 dst_sel:DWORD dst_unused:UNUSED_PAD src0_sel:WORD_1
	v_sub_f32_e32 v57, v57, v104
	v_sub_f32_e32 v56, v56, v104
	v_sub_f32_e32 v59, v59, v104
	v_sub_f32_e32 v58, v58, v104
	v_pk_mul_f32 v[58:59], v[104:105], v[58:59] op_sel:[1,0]
	v_pk_mul_f32 v[56:57], v[104:105], v[56:57] op_sel:[1,0]
	v_pk_fma_f32 v[58:59], v[196:197], v[58:59], v[200:201]
	v_pk_fma_f32 v[56:57], v[198:199], v[56:57], v[202:203]
	v_pk_fma_f32 v[54:55], v[54:55], v[126:127], v[58:59]
	v_pk_fma_f32 v[52:53], v[52:53], v[124:125], v[56:57]
	v_sub_f32_e32 v57, v63, v104
	v_sub_f32_e32 v56, v62, v104
	v_sub_f32_e32 v59, v85, v104
	v_sub_f32_e32 v58, v84, v104
	v_pk_mul_f32 v[58:59], v[104:105], v[58:59] op_sel:[1,0]
	v_pk_mul_f32 v[56:57], v[104:105], v[56:57] op_sel:[1,0]
	v_pk_fma_f32 v[58:59], v[188:189], v[58:59], v[192:193]
	v_pk_fma_f32 v[56:57], v[190:191], v[56:57], v[194:195]
	v_pk_fma_f32 v[58:59], v[50:51], v[110:111], v[58:59]
	v_pk_fma_f32 v[50:51], v[48:49], v[108:109], v[56:57]
	v_cvt_pk_f16_f32 v48, v52, v53
	v_cvt_pk_f16_f32 v49, v54, v55
	v_cvt_pk_f16_f32 v50, v50, v51
	v_cvt_pk_f16_f32 v51, v58, v59
	global_store_dwordx4 v[60:61], v[48:51], off offset:256
	v_cvt_f32_f16_e32 v52, v94
	v_cvt_f32_f16_sdwa v53, v94 dst_sel:DWORD dst_unused:UNUSED_PAD src0_sel:WORD_1
	v_cvt_f32_f16_e32 v48, v92
;     __device__ __forceinline__ void operator()(const AccT& acc, const pg8::Unit& u, int wr, int wc, int fr, int fq) const {
;     ...
;             for (int m = 0; m < 4; ++m) { const int row = row0 + ai * 128 + m * 16; const size_t off = (size_t)row * D + col0; const f32x2 st = stv[m];
; #pragma unroll
;                 for (int bj = 0; bj < 2; ++bj) { float uf[8]; unpack_h8(uraw[m][bj], uf);
;                     const f32x4 ua = {uf[0], uf[1], uf[2], uf[3]}, ub = {uf[4], uf[5], uf[6], uf[7]};
;                     const f32x4 a = ((ua - st.x) * st.y) * lg[bj][0] + lbv[bj][0] + gv[bj][0] * acc[ai][bj][m][0], b = ((ub - st.x) * st.y) * lg[bj][1] + lbv[bj][1] + gv[bj][1] * acc[ai][bj][m][1];
;                     u32x4 w; w.x = pk_h2(a[0], a[1]); w.y = pk_h2(a[2], a[3]); w.z = pk_h2(b[0], b[1]); w.w = pk_h2(b[2], b[3]);
;                     *(u32x4*)(U2 + off + bj * 128) = w; } }
	v_cvt_f32_f16_sdwa v49, v92 dst_sel:DWORD dst_unused:UNUSED_PAD src0_sel:WORD_1
	v_cvt_f32_f16_e32 v50, v93
	v_cvt_f32_f16_sdwa v51, v93 dst_sel:DWORD dst_unused:UNUSED_PAD src0_sel:WORD_1
	v_cvt_f32_f16_e32 v54, v95
	v_cvt_f32_f16_sdwa v55, v95 dst_sel:DWORD dst_unused:UNUSED_PAD src0_sel:WORD_1
	v_sub_f32_e32 v49, v49, v116
	v_sub_f32_e32 v48, v48, v116
	v_sub_f32_e32 v51, v51, v116
	v_sub_f32_e32 v50, v50, v116
	v_pk_mul_f32 v[50:51], v[116:117], v[50:51] op_sel:[1,0]
	v_pk_mul_f32 v[48:49], v[116:117], v[48:49] op_sel:[1,0]
	v_pk_fma_f32 v[50:51], v[204:205], v[50:51], v[216:217]
	v_pk_fma_f32 v[48:49], v[206:207], v[48:49], v[218:219]
	v_pk_fma_f32 v[46:47], v[46:47], v[130:131], v[50:51]
	v_pk_fma_f32 v[44:45], v[44:45], v[128:129], v[48:49]
	v_sub_f32_e32 v49, v53, v116
	v_sub_f32_e32 v48, v52, v116
	v_sub_f32_e32 v51, v55, v116
	v_sub_f32_e32 v50, v54, v116
	v_pk_mul_f32 v[50:51], v[116:117], v[50:51] op_sel:[1,0]
	v_pk_mul_f32 v[48:49], v[116:117], v[48:49] op_sel:[1,0]
	v_pk_fma_f32 v[50:51], v[208:209], v[50:51], v[212:213]
	v_pk_fma_f32 v[48:49], v[210:211], v[48:49], v[214:215]
	v_pk_fma_f32 v[50:51], v[42:43], v[114:115], v[50:51]
	v_pk_fma_f32 v[42:43], v[40:41], v[112:113], v[48:49]
	v_cvt_pk_f16_f32 v40, v44, v45
	v_lshl_add_u64 v[44:45], s[16:17], 0, v[118:119]
	v_cvt_pk_f16_f32 v41, v46, v47
	v_cvt_pk_f16_f32 v42, v42, v43
	v_cvt_pk_f16_f32 v43, v50, v51
	v_lshl_add_u64 v[44:45], v[44:45], 0, v[220:221]
	global_store_dwordx4 v[44:45], v[40:43], off
	v_cvt_f32_f16_e32 v46, v98
	v_cvt_f32_f16_sdwa v47, v98 dst_sel:DWORD dst_unused:UNUSED_PAD src0_sel:WORD_1
	v_cvt_f32_f16_e32 v40, v96
	v_cvt_f32_f16_sdwa v41, v96 dst_sel:DWORD dst_unused:UNUSED_PAD src0_sel:WORD_1
	v_cvt_f32_f16_e32 v42, v97
	v_cvt_f32_f16_sdwa v43, v97 dst_sel:DWORD dst_unused:UNUSED_PAD src0_sel:WORD_1
	v_cvt_f32_f16_e32 v48, v99
	v_cvt_f32_f16_sdwa v49, v99 dst_sel:DWORD dst_unused:UNUSED_PAD src0_sel:WORD_1
	v_sub_f32_e32 v41, v41, v116
	v_sub_f32_e32 v40, v40, v116
	v_sub_f32_e32 v43, v43, v116
	v_sub_f32_e32 v42, v42, v116
	v_pk_mul_f32 v[42:43], v[116:117], v[42:43] op_sel:[1,0]
	v_pk_mul_f32 v[40:41], v[116:117], v[40:41] op_sel:[1,0]
	v_pk_fma_f32 v[42:43], v[196:197], v[42:43], v[200:201]
	v_pk_fma_f32 v[40:41], v[198:199], v[40:41], v[202:203]
	v_pk_fma_f32 v[38:39], v[38:39], v[126:127], v[42:43]
	v_pk_fma_f32 v[36:37], v[36:37], v[124:125], v[40:41]
	v_sub_f32_e32 v41, v47, v116
	v_sub_f32_e32 v40, v46, v116
	v_sub_f32_e32 v43, v49, v116
	v_sub_f32_e32 v42, v48, v116
	v_pk_mul_f32 v[42:43], v[116:117], v[42:43] op_sel:[1,0]
	v_pk_mul_f32 v[40:41], v[116:117], v[40:41] op_sel:[1,0]
	v_pk_fma_f32 v[42:43], v[188:189], v[42:43], v[192:193]
	v_pk_fma_f32 v[40:41], v[190:191], v[40:41], v[194:195]
	v_pk_fma_f32 v[42:43], v[34:35], v[110:111], v[42:43]
	v_pk_fma_f32 v[34:35], v[32:33], v[108:109], v[40:41]
	v_cvt_pk_f16_f32 v32, v36, v37
	v_cvt_pk_f16_f32 v33, v38, v39
	v_cvt_pk_f16_f32 v34, v34, v35
	v_cvt_pk_f16_f32 v35, v42, v43
	global_store_dwordx4 v[44:45], v[32:35], off offset:256
	v_cvt_f32_f16_e32 v36, v102
	v_cvt_f32_f16_sdwa v37, v102 dst_sel:DWORD dst_unused:UNUSED_PAD src0_sel:WORD_1
	v_cvt_f32_f16_e32 v32, v100
	v_cvt_f32_f16_sdwa v33, v100 dst_sel:DWORD dst_unused:UNUSED_PAD src0_sel:WORD_1
	v_cvt_f32_f16_e32 v34, v101
	v_cvt_f32_f16_sdwa v35, v101 dst_sel:DWORD dst_unused:UNUSED_PAD src0_sel:WORD_1
	v_cvt_f32_f16_e32 v38, v103
	v_cvt_f32_f16_sdwa v39, v103 dst_sel:DWORD dst_unused:UNUSED_PAD src0_sel:WORD_1
	v_sub_f32_e32 v33, v33, v80
	v_sub_f32_e32 v32, v32, v80
	v_sub_f32_e32 v35, v35, v80
	v_sub_f32_e32 v34, v34, v80
	v_pk_mul_f32 v[34:35], v[80:81], v[34:35] op_sel:[1,0]
	v_pk_mul_f32 v[32:33], v[80:81], v[32:33] op_sel:[1,0]
	v_pk_fma_f32 v[34:35], v[204:205], v[34:35], v[216:217]
	v_pk_fma_f32 v[32:33], v[206:207], v[32:33], v[218:219]
	v_pk_fma_f32 v[30:31], v[30:31], v[130:131], v[34:35]
	v_pk_fma_f32 v[28:29], v[28:29], v[128:129], v[32:33]
	v_sub_f32_e32 v33, v37, v80
	v_sub_f32_e32 v32, v36, v80
	v_sub_f32_e32 v35, v39, v80
	v_sub_f32_e32 v34, v38, v80
	v_pk_mul_f32 v[34:35], v[80:81], v[34:35] op_sel:[1,0]
	v_pk_mul_f32 v[32:33], v[80:81], v[32:33] op_sel:[1,0]
	v_pk_fma_f32 v[34:35], v[208:209], v[34:35], v[212:213]
	v_pk_fma_f32 v[32:33], v[210:211], v[32:33], v[214:215]
	v_pk_fma_f32 v[34:35], v[26:27], v[114:115], v[34:35]
	v_pk_fma_f32 v[26:27], v[24:25], v[112:113], v[32:33]
	v_cvt_pk_f16_f32 v24, v28, v29
	v_lshl_add_u64 v[28:29], s[16:17], 0, v[82:83]
	v_cvt_pk_f16_f32 v25, v30, v31
	v_cvt_pk_f16_f32 v26, v26, v27
	v_cvt_pk_f16_f32 v27, v34, v35
	v_lshl_add_u64 v[28:29], v[28:29], 0, v[220:221]
	global_store_dwordx4 v[28:29], v[24:27], off
	v_cvt_f32_f16_e32 v30, v74
; #define PG8_WAIT_V(n) asm volatile("s_waitcnt vmcnt(" #n ")" ::: "memory")
; #define PG8_BAR __builtin_amdgcn_s_barrier()
; template <class Epi, class Sched>
; __device__ __forceinline__ void gemm_phase(PG8_LAS unsigned char* lds, const Gemm g, const Sched& S, const Epi& E) {
;     ...
;     PG8_WAIT_V(0);
;     if (wr == 0) PG8_BAR;
;     PG8_BAR;
;     __device__ __forceinline__ void operator()(const AccT& acc, const pg8::Unit& u, int wr, int wc, int fr, int fq) const {
;     ...
;             for (int m = 0; m < 4; ++m) { const int row = row0 + ai * 128 + m * 16; const size_t off = (size_t)row * D + col0; const f32x2 st = stv[m];
; #pragma unroll
;                 for (int bj = 0; bj < 2; ++bj) { float uf[8]; unpack_h8(uraw[m][bj], uf);
;                     const f32x4 ua = {uf[0], uf[1], uf[2], uf[3]}, ub = {uf[4], uf[5], uf[6], uf[7]};
;                     const f32x4 a = ((ua - st.x) * st.y) * lg[bj][0] + lbv[bj][0] + gv[bj][0] * acc[ai][bj][m][0], b = ((ub - st.x) * st.y) * lg[bj][1] + lbv[bj][1] + gv[bj][1] * acc[ai][bj][m][1];
;                     u32x4 w; w.x = pk_h2(a[0], a[1]); w.y = pk_h2(a[2], a[3]); w.z = pk_h2(b[0], b[1]); w.w = pk_h2(b[2], b[3]);
;                     *(u32x4*)(U2 + off + bj * 128) = w; } }
	v_cvt_f32_f16_sdwa v31, v74 dst_sel:DWORD dst_unused:UNUSED_PAD src0_sel:WORD_1
	v_cvt_f32_f16_e32 v24, v72
	v_cvt_f32_f16_sdwa v25, v72 dst_sel:DWORD dst_unused:UNUSED_PAD src0_sel:WORD_1
	v_cvt_f32_f16_e32 v26, v73
	v_cvt_f32_f16_sdwa v27, v73 dst_sel:DWORD dst_unused:UNUSED_PAD src0_sel:WORD_1
	v_cvt_f32_f16_e32 v32, v75
	v_cvt_f32_f16_sdwa v33, v75 dst_sel:DWORD dst_unused:UNUSED_PAD src0_sel:WORD_1
	v_sub_f32_e32 v25, v25, v80
	v_sub_f32_e32 v24, v24, v80
	v_sub_f32_e32 v27, v27, v80
	v_sub_f32_e32 v26, v26, v80
	v_pk_mul_f32 v[26:27], v[80:81], v[26:27] op_sel:[1,0]
	v_pk_mul_f32 v[24:25], v[80:81], v[24:25] op_sel:[1,0]
	v_pk_fma_f32 v[26:27], v[196:197], v[26:27], v[200:201]
	v_pk_fma_f32 v[24:25], v[198:199], v[24:25], v[202:203]
	v_pk_fma_f32 v[22:23], v[22:23], v[126:127], v[26:27]
	v_pk_fma_f32 v[20:21], v[20:21], v[124:125], v[24:25]
	v_sub_f32_e32 v25, v31, v80
	v_sub_f32_e32 v24, v30, v80
	v_sub_f32_e32 v27, v33, v80
	v_sub_f32_e32 v26, v32, v80
	v_pk_mul_f32 v[26:27], v[80:81], v[26:27] op_sel:[1,0]
	v_pk_mul_f32 v[24:25], v[80:81], v[24:25] op_sel:[1,0]
	v_pk_fma_f32 v[26:27], v[188:189], v[26:27], v[192:193]
	v_pk_fma_f32 v[24:25], v[190:191], v[24:25], v[194:195]
	v_pk_fma_f32 v[26:27], v[18:19], v[110:111], v[26:27]
	v_pk_fma_f32 v[18:19], v[16:17], v[108:109], v[24:25]
	v_cvt_pk_f16_f32 v16, v20, v21
	v_cvt_pk_f16_f32 v17, v22, v23
	v_cvt_pk_f16_f32 v18, v18, v19
	v_cvt_pk_f16_f32 v19, v26, v27
	global_store_dwordx4 v[28:29], v[16:19], off offset:256
	v_cvt_f32_f16_e32 v20, v70
	v_cvt_f32_f16_sdwa v21, v70 dst_sel:DWORD dst_unused:UNUSED_PAD src0_sel:WORD_1
	v_cvt_f32_f16_e32 v16, v68
	v_cvt_f32_f16_sdwa v17, v68 dst_sel:DWORD dst_unused:UNUSED_PAD src0_sel:WORD_1
	v_cvt_f32_f16_e32 v18, v69
	v_cvt_f32_f16_sdwa v19, v69 dst_sel:DWORD dst_unused:UNUSED_PAD src0_sel:WORD_1
	v_cvt_f32_f16_e32 v22, v71
	v_cvt_f32_f16_sdwa v23, v71 dst_sel:DWORD dst_unused:UNUSED_PAD src0_sel:WORD_1
	v_sub_f32_e32 v17, v17, v76
	v_sub_f32_e32 v16, v16, v76
	v_sub_f32_e32 v19, v19, v76
	v_sub_f32_e32 v18, v18, v76
	v_pk_mul_f32 v[18:19], v[76:77], v[18:19] op_sel:[1,0]
	v_pk_mul_f32 v[16:17], v[76:77], v[16:17] op_sel:[1,0]
	v_pk_fma_f32 v[18:19], v[204:205], v[18:19], v[216:217]
	v_pk_fma_f32 v[16:17], v[206:207], v[16:17], v[218:219]
	v_pk_fma_f32 v[14:15], v[14:15], v[130:131], v[18:19]
	v_pk_fma_f32 v[12:13], v[12:13], v[128:129], v[16:17]
	v_sub_f32_e32 v17, v21, v76
	v_sub_f32_e32 v16, v20, v76
	v_sub_f32_e32 v19, v23, v76
	v_sub_f32_e32 v18, v22, v76
	v_pk_mul_f32 v[18:19], v[76:77], v[18:19] op_sel:[1,0]
	v_pk_mul_f32 v[16:17], v[76:77], v[16:17] op_sel:[1,0]
	v_pk_fma_f32 v[18:19], v[208:209], v[18:19], v[212:213]
	v_pk_fma_f32 v[16:17], v[210:211], v[16:17], v[214:215]
	v_pk_fma_f32 v[18:19], v[10:11], v[114:115], v[18:19]
	v_pk_fma_f32 v[10:11], v[8:9], v[112:113], v[16:17]
	v_cvt_pk_f16_f32 v8, v12, v13
	v_lshl_add_u64 v[12:13], s[16:17], 0, v[78:79]
	v_cvt_pk_f16_f32 v9, v14, v15
	v_cvt_pk_f16_f32 v10, v10, v11
	v_cvt_pk_f16_f32 v11, v18, v19
	v_lshl_add_u64 v[12:13], v[12:13], 0, v[220:221]
	global_store_dwordx4 v[12:13], v[8:11], off
	v_cvt_f32_f16_e32 v14, v66
	v_cvt_f32_f16_sdwa v15, v66 dst_sel:DWORD dst_unused:UNUSED_PAD src0_sel:WORD_1
	v_cvt_f32_f16_e32 v8, v64
	v_cvt_f32_f16_sdwa v9, v64 dst_sel:DWORD dst_unused:UNUSED_PAD src0_sel:WORD_1
	v_cvt_f32_f16_e32 v10, v65
	v_cvt_f32_f16_sdwa v11, v65 dst_sel:DWORD dst_unused:UNUSED_PAD src0_sel:WORD_1
	v_cvt_f32_f16_e32 v16, v67
	v_cvt_f32_f16_sdwa v17, v67 dst_sel:DWORD dst_unused:UNUSED_PAD src0_sel:WORD_1
	v_sub_f32_e32 v9, v9, v76
	v_sub_f32_e32 v8, v8, v76
	v_sub_f32_e32 v11, v11, v76
	v_sub_f32_e32 v10, v10, v76
	v_pk_mul_f32 v[10:11], v[76:77], v[10:11] op_sel:[1,0]
	v_pk_mul_f32 v[8:9], v[76:77], v[8:9] op_sel:[1,0]
	v_pk_fma_f32 v[10:11], v[196:197], v[10:11], v[200:201]
	v_pk_fma_f32 v[8:9], v[198:199], v[8:9], v[202:203]
	v_pk_fma_f32 v[6:7], v[6:7], v[126:127], v[10:11]
	v_pk_fma_f32 v[4:5], v[4:5], v[124:125], v[8:9]
	v_sub_f32_e32 v9, v15, v76
	v_sub_f32_e32 v8, v14, v76
	v_sub_f32_e32 v11, v17, v76
	v_sub_f32_e32 v10, v16, v76
	v_pk_mul_f32 v[10:11], v[76:77], v[10:11] op_sel:[1,0]
	v_pk_mul_f32 v[8:9], v[76:77], v[8:9] op_sel:[1,0]
	v_pk_fma_f32 v[10:11], v[188:189], v[10:11], v[192:193]
	v_pk_fma_f32 v[8:9], v[190:191], v[8:9], v[194:195]
	v_pk_fma_f32 v[10:11], v[2:3], v[110:111], v[10:11]
	v_pk_fma_f32 v[2:3], v[0:1], v[108:109], v[8:9]
	v_cvt_pk_f16_f32 v0, v4, v5
	v_cvt_pk_f16_f32 v1, v6, v7
	v_cvt_pk_f16_f32 v2, v2, v3
	v_cvt_pk_f16_f32 v3, v10, v11
	global_store_dwordx4 v[12:13], v[0:3], off offset:256
	s_cbranch_vccz .LBB0_871
	s_waitcnt vmcnt(0)
	s_cmpk_gt_u32 s21, 0xff
	s_cbranch_scc1 .LBB0_886
	s_barrier
